# MLA softmax row-sum accumulated with v_pk_add_f32 into two partial sums (exp results in aligned pairs), 15 fewer VALU per step
# baseline (speedup 1.0000x reference)
.LBB0_546:
	s_or_b64 exec, exec, s[24:25]
	global_load_dwordx4 v[206:209], v[252:253], off
	s_mov_b64 s[0:1], 0x10000
	v_lshl_add_u64 v[250:251], v[250:251], 0, s[0:1]
	v_lshl_add_u64 v[252:253], v[252:253], 0, s[0:1]
	v_exp_f32_e32 v82, v82
	v_exp_f32_e32 v83, v83
	v_mfma_f32_32x32x16_bf16 v[114:129], v[98:101], v[150:153], v[66:81]
	v_exp_f32_e32 v84, v84
	v_exp_f32_e32 v85, v85
	v_cvt_pk_bf16_f32 v34, v82, v83
	v_pk_add_f32 v[218:219], v[82:83], v[84:85]
	v_cvt_pk_bf16_f32 v35, v84, v85
	v_exp_f32_e32 v86, v86
	v_mfma_f32_32x32x16_bf16 v[98:113], v[202:205], v[150:153], v[66:81]
	v_exp_f32_e32 v87, v87
	v_exp_f32_e32 v88, v88
	v_exp_f32_e32 v89, v89
	v_pk_add_f32 v[218:219], v[86:87], v[218:219]
	v_cvt_pk_bf16_f32 v36, v86, v87
	v_pk_add_f32 v[218:219], v[88:89], v[218:219]
	v_cvt_pk_bf16_f32 v37, v88, v89
	v_exp_f32_e32 v90, v90
	v_exp_f32_e32 v91, v91
	v_mfma_f32_32x32x16_bf16 v[114:129], v[198:201], v[146:149], v[114:129]
	v_exp_f32_e32 v93, v93
	v_pk_add_f32 v[218:219], v[90:91], v[218:219]
	v_cvt_pk_bf16_f32 v38, v90, v91
	v_exp_f32_e32 v92, v92
	s_nop 0
	v_pk_add_f32 v[218:219], v[92:93], v[218:219]
	v_cvt_pk_bf16_f32 v39, v92, v93
	v_exp_f32_e32 v94, v94
	v_exp_f32_e32 v95, v95
	v_mfma_f32_32x32x16_bf16 v[98:113], v[194:197], v[146:149], v[98:113]
	v_exp_f32_e32 v97, v97
	v_pk_add_f32 v[218:219], v[94:95], v[218:219]
	v_cvt_pk_bf16_f32 v40, v94, v95
	v_exp_f32_e32 v96, v96
	s_nop 0
	v_pk_add_f32 v[218:219], v[96:97], v[218:219]
	v_cvt_pk_bf16_f32 v41, v96, v97
	v_mfma_f32_32x32x16_bf16 v[114:129], v[190:193], v[142:145], v[114:129]
	ds_read_b64_tr_b16 v[82:83], v231 offset:26624
	ds_read_b64_tr_b16 v[84:85], v231 offset:27392
	ds_read_b64_tr_b16 v[46:47], v231 offset:26688
	ds_read_b64_tr_b16 v[48:49], v231 offset:27456
	v_exp_f32_e32 v42, v50
	v_exp_f32_e32 v43, v51
	s_nop 0
	v_pk_add_f32 v[218:219], v[42:43], v[218:219]
	v_cvt_pk_bf16_f32 v42, v42, v43
	v_mfma_f32_32x32x16_bf16 v[98:113], v[186:189], v[142:145], v[98:113]
	v_exp_f32_e32 v52, v52
	v_exp_f32_e32 v53, v53
	ds_read_b64_tr_b16 v[86:87], v231 offset:29696
	ds_read_b64_tr_b16 v[88:89], v231 offset:30464
	v_pk_add_f32 v[218:219], v[52:53], v[218:219]
	v_cvt_pk_bf16_f32 v43, v52, v53
	v_mfma_f32_32x32x16_bf16 v[114:129], v[182:185], v[138:141], v[114:129]
	v_exp_f32_e32 v54, v54
	v_exp_f32_e32 v55, v55
	ds_read_b64_tr_b16 v[90:91], v231 offset:29760
	ds_read_b64_tr_b16 v[92:93], v231 offset:30528
	v_pk_add_f32 v[218:219], v[54:55], v[218:219]
	v_cvt_pk_bf16_f32 v44, v54, v55
	v_mfma_f32_32x32x16_bf16 v[98:113], v[178:181], v[138:141], v[98:113]
	v_exp_f32_e32 v56, v56
	v_exp_f32_e32 v57, v57
	ds_read_b64_tr_b16 v[94:95], v231 offset:32768
	ds_read_b64_tr_b16 v[96:97], v231 offset:33536
	v_pk_add_f32 v[218:219], v[56:57], v[218:219]
	v_cvt_pk_bf16_f32 v45, v56, v57
	v_mfma_f32_32x32x16_bf16 v[114:129], v[174:177], v[134:137], v[114:129]
	v_exp_f32_e32 v50, v58
	v_exp_f32_e32 v51, v59
	ds_read_b64_tr_b16 v[210:211], v231 offset:32832
	ds_read_b64_tr_b16 v[212:213], v231 offset:33600
	v_pk_add_f32 v[218:219], v[50:51], v[218:219]
	v_cvt_pk_bf16_f32 v54, v50, v51
	v_mfma_f32_32x32x16_bf16 v[98:113], v[170:173], v[134:137], v[98:113]
	v_exp_f32_e32 v50, v60
	v_exp_f32_e32 v51, v61
	ds_read_b64_tr_b16 v[58:59], v231 offset:35840
	ds_read_b64_tr_b16 v[60:61], v231 offset:36608
	v_pk_add_f32 v[218:219], v[50:51], v[218:219]
	v_cvt_pk_bf16_f32 v55, v50, v51
	v_mfma_f32_32x32x16_bf16 v[114:129], v[166:169], v[130:133], v[114:129]
	v_exp_f32_e32 v50, v62
	v_exp_f32_e32 v51, v63
	ds_read_b64_tr_b16 v[214:215], v231 offset:35904
	ds_read_b64_tr_b16 v[216:217], v231 offset:36672
	v_pk_add_f32 v[218:219], v[50:51], v[218:219]
	v_cvt_pk_bf16_f32 v56, v50, v51
	v_mfma_f32_32x32x16_bf16 v[98:113], v[158:161], v[130:133], v[98:113]
	v_exp_f32_e32 v50, v64
	v_exp_f32_e32 v51, v65
	s_nop 0
	v_pk_add_f32 v[218:219], v[50:51], v[218:219]
	v_cvt_pk_bf16_f32 v57, v50, v51
	v_add_f32_e32 v62, v218, v219
	s_waitcnt lgkmcnt(14)
	v_mfma_f32_32x32x16_bf16 v[18:33], v[82:85], v[34:37], v[18:33]
	ds_read_b128 v[50:53], v233
	ds_read_b128 v[198:201], v233 offset:6656
	v_add_f32_e32 v0, v242, v62
	s_waitcnt lgkmcnt(14)
	v_mfma_f32_32x32x16_bf16 v[2:17], v[46:49], v[34:37], v[2:17]
	ds_read_b128 v[202:205], v233 offset:32
	ds_read_b128 v[194:197], v233 offset:6688
	s_waitcnt lgkmcnt(14)
	v_mfma_f32_32x32x16_bf16 v[18:33], v[86:89], v[38:41], v[18:33]
	ds_read_b128 v[190:193], v233 offset:64
	ds_read_b128 v[186:189], v233 offset:6720
	s_waitcnt lgkmcnt(14)
	v_mfma_f32_32x32x16_bf16 v[2:17], v[90:93], v[38:41], v[2:17]
	ds_read_b128 v[182:185], v233 offset:96
	ds_read_b128 v[178:181], v233 offset:6752
	s_waitcnt lgkmcnt(14)
	v_mfma_f32_32x32x16_bf16 v[18:33], v[94:97], v[42:45], v[18:33]
	ds_read_b128 v[174:177], v233 offset:128
	ds_read_b128 v[170:173], v233 offset:6784
	s_waitcnt lgkmcnt(14)
	v_mfma_f32_32x32x16_bf16 v[2:17], v[210:213], v[42:45], v[2:17]
	ds_read_b128 v[166:169], v233 offset:160
	ds_read_b128 v[158:161], v233 offset:6816
	s_waitcnt lgkmcnt(14)
	v_mfma_f32_32x32x16_bf16 v[18:33], v[58:61], v[54:57], v[18:33]
	s_waitcnt lgkmcnt(12)
	v_mfma_f32_32x32x16_bf16 v[2:17], v[214:217], v[54:57], v[2:17]
	v_mov_b32_e32 v34, v62
	s_nop 1
	v_permlane32_swap_b32_e32 v62, v34
	v_max_f32_e32 v34, v62, v34
	v_cmp_lt_f32_e32 vcc, s74, v34
	s_cbranch_vccz .LBB0_558
	v_frexp_exp_i32_f32_e32 v34, v34
	v_cvt_f32_i32_e32 v34, v34
	v_cndmask_b32_e32 v35, 0, v34, vcc
	v_exp_f32_e64 v36, -v35
	v_add_f32_e32 v235, v235, v35
	v_xor_b32_e32 v34, 0x80000000, v235
	v_sub_f32_e32 v129, v129, v35
	v_pk_mul_f32 v[32:33], v[32:33], v[36:37] op_sel_hi:[1,0]
	v_pk_mul_f32 v[30:31], v[30:31], v[36:37] op_sel_hi:[1,0]
	v_pk_mul_f32 v[28:29], v[28:29], v[36:37] op_sel_hi:[1,0]
	v_pk_mul_f32 v[26:27], v[26:27], v[36:37] op_sel_hi:[1,0]
	v_pk_mul_f32 v[24:25], v[24:25], v[36:37] op_sel_hi:[1,0]
	v_pk_mul_f32 v[22:23], v[22:23], v[36:37] op_sel_hi:[1,0]
	v_pk_mul_f32 v[20:21], v[20:21], v[36:37] op_sel_hi:[1,0]
	v_pk_mul_f32 v[18:19], v[18:19], v[36:37] op_sel_hi:[1,0]
	v_pk_mul_f32 v[16:17], v[16:17], v[36:37] op_sel_hi:[1,0]
	v_pk_mul_f32 v[14:15], v[14:15], v[36:37] op_sel_hi:[1,0]
	v_pk_mul_f32 v[12:13], v[12:13], v[36:37] op_sel_hi:[1,0]
	v_pk_mul_f32 v[10:11], v[10:11], v[36:37] op_sel_hi:[1,0]
	v_pk_mul_f32 v[8:9], v[8:9], v[36:37] op_sel_hi:[1,0]
	v_pk_mul_f32 v[6:7], v[6:7], v[36:37] op_sel_hi:[1,0]
	v_pk_mul_f32 v[4:5], v[4:5], v[36:37] op_sel_hi:[1,0]
	v_pk_mul_f32 v[2:3], v[2:3], v[36:37] op_sel_hi:[1,0]
	v_sub_f32_e32 v128, v128, v35
	v_sub_f32_e32 v127, v127, v35
	v_sub_f32_e32 v126, v126, v35
	v_sub_f32_e32 v125, v125, v35
	v_sub_f32_e32 v124, v124, v35
	v_sub_f32_e32 v123, v123, v35
	v_sub_f32_e32 v122, v122, v35
	v_sub_f32_e32 v121, v121, v35
	v_sub_f32_e32 v120, v120, v35
	v_sub_f32_e32 v119, v119, v35
	v_sub_f32_e32 v118, v118, v35
	v_sub_f32_e32 v117, v117, v35
	v_sub_f32_e32 v116, v116, v35
	v_sub_f32_e32 v115, v115, v35
	v_sub_f32_e32 v114, v114, v35
	v_sub_f32_e32 v113, v113, v35
	v_sub_f32_e32 v112, v112, v35
	v_sub_f32_e32 v111, v111, v35
	v_sub_f32_e32 v110, v110, v35
	v_sub_f32_e32 v109, v109, v35
	v_sub_f32_e32 v108, v108, v35
	v_sub_f32_e32 v107, v107, v35
	v_sub_f32_e32 v106, v106, v35
	v_sub_f32_e32 v105, v105, v35
	v_sub_f32_e32 v104, v104, v35
	v_sub_f32_e32 v103, v103, v35
	v_sub_f32_e32 v102, v102, v35
	v_sub_f32_e32 v101, v101, v35
	v_sub_f32_e32 v100, v100, v35
	v_sub_f32_e32 v99, v99, v35
	v_sub_f32_e32 v98, v98, v35
	v_mul_f32_e32 v0, v0, v36
	v_mov_b32_e32 v35, v34
	v_mov_b32_e32 v36, v34
	v_mov_b32_e32 v37, v34
	v_mov_b32_e32 v38, v34
	v_mov_b32_e32 v39, v34
	v_mov_b32_e32 v40, v34
	v_mov_b32_e32 v41, v34
	v_mov_b32_e32 v42, v34
	v_mov_b32_e32 v43, v34
	v_mov_b32_e32 v44, v34
	v_mov_b32_e32 v45, v34
	v_mov_b32_e32 v46, v34
	v_mov_b32_e32 v47, v34
	v_mov_b32_e32 v48, v34
	v_mov_b32_e32 v49, v34
	v_mov_b32_e32 v66, v34
	v_mov_b32_e32 v67, v34
	v_mov_b32_e32 v68, v34
	v_mov_b32_e32 v69, v34
	v_mov_b32_e32 v70, v34
	v_mov_b32_e32 v71, v34
	v_mov_b32_e32 v72, v34
	v_mov_b32_e32 v73, v34
	v_mov_b32_e32 v74, v34
	v_mov_b32_e32 v75, v34
	v_mov_b32_e32 v76, v34
	v_mov_b32_e32 v77, v34
	v_mov_b32_e32 v78, v34
	v_mov_b32_e32 v79, v34
	v_mov_b32_e32 v80, v34
	v_mov_b32_e32 v81, v34
	s_waitcnt vmcnt(1)
	ds_write_b128 v232, v[162:165] offset:13312
	s_and_saveexec_b64 s[24:25], s[4:5]

.LBB0_553:
	global_load_dwordx4 v[206:209], v[252:253], off
	s_mov_b64 s[0:1], 0x10000
	v_lshl_add_u64 v[250:251], v[250:251], 0, s[0:1]
	v_lshl_add_u64 v[252:253], v[252:253], 0, s[0:1]
	v_mfma_f32_32x32x16_bf16 v[82:97], v[50:53], v[150:153], v[66:81]
	v_exp_f32_e32 v50, v114
	v_exp_f32_e32 v51, v115
	v_exp_f32_e32 v52, v116
	v_exp_f32_e32 v53, v117
	v_cvt_pk_bf16_f32 v114, v50, v51
	v_pk_add_f32 v[218:219], v[50:51], v[52:53]
	v_cvt_pk_bf16_f32 v115, v52, v53
	v_exp_f32_e32 v116, v118
	v_exp_f32_e32 v117, v119
	v_exp_f32_e32 v118, v120
	v_exp_f32_e32 v119, v121
	v_pk_add_f32 v[218:219], v[116:117], v[218:219]
	v_mfma_f32_32x32x16_bf16 v[50:65], v[198:201], v[150:153], v[66:81]
	v_cvt_pk_bf16_f32 v116, v116, v117
	v_pk_add_f32 v[218:219], v[118:119], v[218:219]
	v_cvt_pk_bf16_f32 v117, v118, v119
	v_exp_f32_e32 v118, v122
	v_exp_f32_e32 v119, v123
	v_mfma_f32_32x32x16_bf16 v[82:97], v[202:205], v[146:149], v[82:97]
	v_exp_f32_e32 v121, v125
	v_pk_add_f32 v[218:219], v[118:119], v[218:219]
	v_cvt_pk_bf16_f32 v118, v118, v119
	v_exp_f32_e32 v120, v124
	s_nop 0
	v_pk_add_f32 v[218:219], v[120:121], v[218:219]
	v_cvt_pk_bf16_f32 v119, v120, v121
	v_exp_f32_e32 v126, v126
	v_exp_f32_e32 v127, v127
	v_mfma_f32_32x32x16_bf16 v[50:65], v[194:197], v[146:149], v[50:65]
	v_pk_add_f32 v[218:219], v[126:127], v[218:219]
	v_cvt_pk_bf16_f32 v120, v126, v127
	v_exp_f32_e32 v128, v128
	v_exp_f32_e32 v129, v129
	s_nop 0
	v_pk_add_f32 v[218:219], v[128:129], v[218:219]
	v_cvt_pk_bf16_f32 v121, v128, v129
	v_mfma_f32_32x32x16_bf16 v[82:97], v[190:193], v[142:145], v[82:97]
	ds_read_b64_tr_b16 v[190:191], v231 offset:38912
	ds_read_b64_tr_b16 v[192:193], v231 offset:39680
	ds_read_b64_tr_b16 v[126:127], v231 offset:38976
	ds_read_b64_tr_b16 v[128:129], v231 offset:39744
	v_exp_f32_e32 v98, v98
	v_exp_f32_e32 v99, v99
	s_nop 0
	v_pk_add_f32 v[218:219], v[98:99], v[218:219]
	v_cvt_pk_bf16_f32 v122, v98, v99
	v_mfma_f32_32x32x16_bf16 v[50:65], v[186:189], v[142:145], v[50:65]
	v_exp_f32_e32 v98, v100
	v_exp_f32_e32 v99, v101
	ds_read_b64_tr_b16 v[186:187], v231 offset:41984
	ds_read_b64_tr_b16 v[188:189], v231 offset:42752
	v_pk_add_f32 v[218:219], v[98:99], v[218:219]
	v_cvt_pk_bf16_f32 v123, v98, v99
	v_mfma_f32_32x32x16_bf16 v[82:97], v[182:185], v[138:141], v[82:97]
	v_exp_f32_e32 v98, v102
	v_exp_f32_e32 v99, v103
	ds_read_b64_tr_b16 v[182:183], v231 offset:42048
	ds_read_b64_tr_b16 v[184:185], v231 offset:42816
	v_pk_add_f32 v[218:219], v[98:99], v[218:219]
	v_cvt_pk_bf16_f32 v124, v98, v99
	v_mfma_f32_32x32x16_bf16 v[50:65], v[178:181], v[138:141], v[50:65]
	v_exp_f32_e32 v98, v104
	v_exp_f32_e32 v99, v105
	ds_read_b64_tr_b16 v[210:211], v231 offset:45056
	ds_read_b64_tr_b16 v[212:213], v231 offset:45824
	v_pk_add_f32 v[218:219], v[98:99], v[218:219]
	v_cvt_pk_bf16_f32 v125, v98, v99
	v_mfma_f32_32x32x16_bf16 v[82:97], v[174:177], v[134:137], v[82:97]
	v_exp_f32_e32 v98, v106
	v_exp_f32_e32 v99, v107
	ds_read_b64_tr_b16 v[214:215], v231 offset:45120
	ds_read_b64_tr_b16 v[216:217], v231 offset:45888
	v_pk_add_f32 v[218:219], v[98:99], v[218:219]
	v_cvt_pk_bf16_f32 v102, v98, v99
	v_mfma_f32_32x32x16_bf16 v[50:65], v[170:173], v[134:137], v[50:65]
	v_exp_f32_e32 v98, v108
	v_exp_f32_e32 v99, v109
	ds_read_b64_tr_b16 v[106:107], v231 offset:48128
	ds_read_b64_tr_b16 v[108:109], v231 offset:48896
	v_pk_add_f32 v[218:219], v[98:99], v[218:219]
	v_cvt_pk_bf16_f32 v103, v98, v99
	v_mfma_f32_32x32x16_bf16 v[82:97], v[166:169], v[130:133], v[82:97]
	v_exp_f32_e32 v98, v110
	v_exp_f32_e32 v99, v111
	ds_read_b64_tr_b16 v[244:245], v231 offset:48192
	ds_read_b64_tr_b16 v[246:247], v231 offset:48960
	v_pk_add_f32 v[218:219], v[98:99], v[218:219]
	v_cvt_pk_bf16_f32 v104, v98, v99
	v_mfma_f32_32x32x16_bf16 v[50:65], v[158:161], v[130:133], v[50:65]
	v_exp_f32_e32 v98, v112
	v_exp_f32_e32 v99, v113
	s_nop 0
	v_pk_add_f32 v[218:219], v[98:99], v[218:219]
	v_cvt_pk_bf16_f32 v105, v98, v99
	v_add_f32_e32 v110, v218, v219
	s_waitcnt lgkmcnt(14)
	v_mfma_f32_32x32x16_bf16 v[18:33], v[190:193], v[114:117], v[18:33]
	ds_read_b128 v[98:101], v233 offset:13312
	ds_read_b128 v[202:205], v233 offset:19968
	v_add_f32_e32 v242, v0, v110
	s_waitcnt lgkmcnt(14)
	v_mfma_f32_32x32x16_bf16 v[2:17], v[126:129], v[114:117], v[2:17]
	ds_read_b128 v[198:201], v233 offset:13344
	ds_read_b128 v[194:197], v233 offset:20000
	s_waitcnt lgkmcnt(14)
	v_mfma_f32_32x32x16_bf16 v[18:33], v[186:189], v[118:121], v[18:33]
	ds_read_b128 v[190:193], v233 offset:13376
	ds_read_b128 v[186:189], v233 offset:20032
	s_waitcnt lgkmcnt(14)
	v_mfma_f32_32x32x16_bf16 v[2:17], v[182:185], v[118:121], v[2:17]
	ds_read_b128 v[182:185], v233 offset:13408
	ds_read_b128 v[178:181], v233 offset:20064
	s_waitcnt lgkmcnt(14)
	v_mfma_f32_32x32x16_bf16 v[18:33], v[210:213], v[122:125], v[18:33]
	ds_read_b128 v[174:177], v233 offset:13440
	ds_read_b128 v[170:173], v233 offset:20096
	s_waitcnt lgkmcnt(14)
	v_mfma_f32_32x32x16_bf16 v[2:17], v[214:217], v[122:125], v[2:17]
	ds_read_b128 v[166:169], v233 offset:13472
	ds_read_b128 v[158:161], v233 offset:20128
	s_waitcnt lgkmcnt(14)
	v_mfma_f32_32x32x16_bf16 v[18:33], v[106:109], v[102:105], v[18:33]
	s_waitcnt lgkmcnt(12)
	v_mfma_f32_32x32x16_bf16 v[2:17], v[244:247], v[102:105], v[2:17]
	v_mov_b32_e32 v0, v110
	s_nop 1
	v_permlane32_swap_b32_e32 v110, v0
	v_max_f32_e32 v0, v110, v0
	v_cmp_lt_f32_e32 vcc, s74, v0
	s_cbranch_vccz .LBB0_555
	v_frexp_exp_i32_f32_e32 v0, v0
	v_cvt_f32_i32_e32 v0, v0
	v_cndmask_b32_e32 v35, 0, v0, vcc
	v_exp_f32_e64 v0, -v35
	v_add_f32_e32 v235, v235, v35
	v_xor_b32_e32 v34, 0x80000000, v235
	v_sub_f32_e32 v97, v97, v35
	v_pk_mul_f32 v[32:33], v[32:33], v[0:1] op_sel_hi:[1,0]
	v_pk_mul_f32 v[30:31], v[30:31], v[0:1] op_sel_hi:[1,0]
	v_pk_mul_f32 v[28:29], v[28:29], v[0:1] op_sel_hi:[1,0]
	v_pk_mul_f32 v[26:27], v[26:27], v[0:1] op_sel_hi:[1,0]
	v_pk_mul_f32 v[24:25], v[24:25], v[0:1] op_sel_hi:[1,0]
	v_pk_mul_f32 v[22:23], v[22:23], v[0:1] op_sel_hi:[1,0]
	v_pk_mul_f32 v[20:21], v[20:21], v[0:1] op_sel_hi:[1,0]
	v_pk_mul_f32 v[18:19], v[18:19], v[0:1] op_sel_hi:[1,0]
	v_pk_mul_f32 v[16:17], v[16:17], v[0:1] op_sel_hi:[1,0]
	v_pk_mul_f32 v[14:15], v[14:15], v[0:1] op_sel_hi:[1,0]
	v_pk_mul_f32 v[12:13], v[12:13], v[0:1] op_sel_hi:[1,0]
	v_pk_mul_f32 v[10:11], v[10:11], v[0:1] op_sel_hi:[1,0]
	v_pk_mul_f32 v[8:9], v[8:9], v[0:1] op_sel_hi:[1,0]
	v_pk_mul_f32 v[6:7], v[6:7], v[0:1] op_sel_hi:[1,0]
	v_pk_mul_f32 v[4:5], v[4:5], v[0:1] op_sel_hi:[1,0]
	v_pk_mul_f32 v[2:3], v[2:3], v[0:1] op_sel_hi:[1,0]
	v_sub_f32_e32 v96, v96, v35
	v_sub_f32_e32 v95, v95, v35
	v_sub_f32_e32 v94, v94, v35
	v_sub_f32_e32 v93, v93, v35
	v_sub_f32_e32 v92, v92, v35
	v_sub_f32_e32 v91, v91, v35
	v_sub_f32_e32 v90, v90, v35
	v_sub_f32_e32 v89, v89, v35
	v_sub_f32_e32 v88, v88, v35
	v_sub_f32_e32 v87, v87, v35
	v_sub_f32_e32 v86, v86, v35
	v_sub_f32_e32 v85, v85, v35
	v_sub_f32_e32 v84, v84, v35
	v_sub_f32_e32 v83, v83, v35
	v_sub_f32_e32 v82, v82, v35
	v_sub_f32_e32 v65, v65, v35
	v_sub_f32_e32 v64, v64, v35
	v_sub_f32_e32 v63, v63, v35
	v_sub_f32_e32 v62, v62, v35
	v_sub_f32_e32 v61, v61, v35
	v_sub_f32_e32 v60, v60, v35
	v_sub_f32_e32 v59, v59, v35
	v_sub_f32_e32 v58, v58, v35
	v_sub_f32_e32 v57, v57, v35
	v_sub_f32_e32 v56, v56, v35
	v_sub_f32_e32 v55, v55, v35
	v_sub_f32_e32 v54, v54, v35
	v_sub_f32_e32 v53, v53, v35
	v_sub_f32_e32 v52, v52, v35
	v_sub_f32_e32 v51, v51, v35
	v_sub_f32_e32 v50, v50, v35
	v_mul_f32_e32 v242, v242, v0
	v_mov_b32_e32 v35, v34
	v_mov_b32_e32 v36, v34
	v_mov_b32_e32 v37, v34
	v_mov_b32_e32 v38, v34
	v_mov_b32_e32 v39, v34
	v_mov_b32_e32 v40, v34
	v_mov_b32_e32 v41, v34
	v_mov_b32_e32 v42, v34
	v_mov_b32_e32 v43, v34
	v_mov_b32_e32 v44, v34
	v_mov_b32_e32 v45, v34
	v_mov_b32_e32 v46, v34
	v_mov_b32_e32 v47, v34
	v_mov_b32_e32 v48, v34
	v_mov_b32_e32 v49, v34
	v_mov_b32_e32 v66, v34
	v_mov_b32_e32 v67, v34
	v_mov_b32_e32 v68, v34
	v_mov_b32_e32 v69, v34
	v_mov_b32_e32 v70, v34
	v_mov_b32_e32 v71, v34
	v_mov_b32_e32 v72, v34
	v_mov_b32_e32 v73, v34
	v_mov_b32_e32 v74, v34
	v_mov_b32_e32 v75, v34
	v_mov_b32_e32 v76, v34
	v_mov_b32_e32 v77, v34
	v_mov_b32_e32 v78, v34
	v_mov_b32_e32 v79, v34
	v_mov_b32_e32 v80, v34
	v_mov_b32_e32 v81, v34
